# v43 + P2 sample loop (rot 1 copy): 8 forget-gate loads batched with counted waits instead of 8 dependent load->vmcnt(0)->sigmoid round trips
# baseline (speedup 1.0000x reference)
; __device__ __forceinline__ void hgrn_sample_loop(Frame& F) {
;     ...
;         if (tid < 128) { const int col = h * HD + tid; const float lb = 1.0f / (1.0f + __expf(F.in[5][512 + col] - F.in[5][col]));
;             float gl[8], kk[8], qq[8]; float run = 0.f;
; #pragma unroll
;             for (int t = 0; t < 8; ++t) { const size_t tok = (size_t)(tok0 + t); const float fz = FZ[tok * 512 + col]; qq[t] = bf2f(PB[tok * PBW + 512 + col]);
;                 const float sg = __builtin_amdgcn_rcpf(1.0f + __builtin_amdgcn_exp2f(-1.4426950408889634f * fz)), f = lb + (1.0f - lb) * sg; kk[t] = 1.0f - f; run += __log2f(f); gl[t] = run; }
.LBB0_284:
	s_andn2_saveexec_b64 s[14:15], s[14:15]
	s_cbranch_execz .LBB0_286
	v_lshl_or_b32 v35, s35, 7, v0
	v_readlane_b32 s16, v238, 4
	v_lshlrev_b32_e32 v36, 2, v35
	v_readlane_b32 s26, v238, 14
	v_readlane_b32 s27, v238, 15
	s_nop 4
	global_load_dword v34, v36, s[26:27] offset:2048
	global_load_dword v38, v36, s[26:27]
	v_readlane_b32 s17, v238, 5
	v_mov_b32_e32 v37, v135
	s_ashr_i32 s5, s4, 31
	v_readlane_b32 s18, v238, 6
	v_readlane_b32 s19, v238, 7
	v_readlane_b32 s20, v238, 8
	v_readlane_b32 s21, v238, 9
	v_readlane_b32 s22, v238, 10
	v_readlane_b32 s23, v238, 11
	v_readlane_b32 s24, v238, 12
	v_readlane_b32 s25, v238, 13
	v_readlane_b32 s28, v238, 16
	v_readlane_b32 s29, v238, 17
	v_readlane_b32 s30, v238, 18
	v_readlane_b32 s31, v238, 19
	v_lshlrev_b32_e32 v35, 1, v35
	s_waitcnt vmcnt(0)
	v_sub_f32_e32 v34, v34, v38
	v_mul_f32_e32 v34, 0x3fb8aa3b, v34
	v_exp_f32_e32 v34, v34
	s_nop 0
	v_add_f32_e32 v34, 1.0, v34
	v_div_scale_f32 v38, s[16:17], v34, v34, 1.0
	v_rcp_f32_e32 v39, v38
	v_readlane_b32 s16, v238, 45
	v_readlane_b32 s17, v238, 46
	v_fma_f32 v40, -v38, v39, 1.0
	v_fmac_f32_e32 v39, v40, v39
	v_div_scale_f32 v40, vcc, 1.0, v34, 1.0
	v_mul_f32_e32 v41, v40, v39
	v_fma_f32 v42, -v38, v41, v40
	v_fmac_f32_e32 v41, v42, v39
	v_fma_f32 v38, -v38, v41, v40
	v_div_fmas_f32 v38, v38, v39, v41
	v_div_fixup_f32 v34, v38, v34, 1.0
	v_lshl_add_u64 v[38:39], s[16:17], 0, v[36:37]
	s_lshl_b64 s[16:17], s[4:5], 11
	v_lshl_add_u64 v[40:41], v[38:39], 0, s[16:17]
	global_load_dword v214, v[40:41], off
	s_lshl_b64 s[16:17], s[4:5], 12
	s_add_u32 s16, s56, s16
	s_addc_u32 s17, s57, s17
	s_or_b32 s18, s4, 1
	s_ashr_i32 s19, s18, 31
	s_lshl_b64 s[20:21], s[18:19], 11
	v_lshl_add_u64 v[40:41], v[38:39], 0, s[20:21]
	s_lshl_b64 s[18:19], s[18:19], 12
	s_add_u32 s18, s56, s18
	s_addc_u32 s19, s57, s19
	s_or_b32 s20, s4, 2
	s_ashr_i32 s21, s20, 31
	s_lshl_b64 s[22:23], s[20:21], 11
	s_lshl_b64 s[20:21], s[20:21], 12
	v_sub_f32_e32 v36, 1.0, v34
	global_load_dword v215, v[40:41], off
	v_lshl_add_u64 v[40:41], v[38:39], 0, s[22:23]
	s_add_u32 s22, s56, s20
	s_addc_u32 s23, s57, s21
	s_or_b32 s20, s4, 3
	s_ashr_i32 s21, s20, 31
	s_lshl_b64 s[24:25], s[20:21], 11
	v_lshl_add_u64 v[42:43], v[38:39], 0, s[24:25]
	s_lshl_b64 s[20:21], s[20:21], 12
	s_add_u32 s20, s56, s20
	s_addc_u32 s21, s57, s21
	s_or_b32 s24, s4, 4
	s_ashr_i32 s25, s24, 31
	s_lshl_b64 s[26:27], s[24:25], 11
	s_lshl_b64 s[24:25], s[24:25], 12
	s_add_u32 s24, s56, s24
	s_addc_u32 s25, s57, s25
	global_load_dword v216, v[40:41], off
	global_load_dword v217, v[42:43], off
	v_lshl_add_u64 v[42:43], v[38:39], 0, s[26:27]
	s_or_b32 s26, s4, 5
	s_ashr_i32 s27, s26, 31
	s_lshl_b64 s[28:29], s[26:27], 11
	v_lshl_add_u64 v[44:45], v[38:39], 0, s[28:29]
	s_lshl_b64 s[26:27], s[26:27], 12
	s_add_u32 s26, s56, s26
	s_addc_u32 s27, s57, s27
	s_or_b32 s28, s4, 6
	s_ashr_i32 s29, s28, 31
	s_lshl_b64 s[30:31], s[28:29], 11
	s_lshl_b64 s[28:29], s[28:29], 12
	s_add_u32 s28, s56, s28
	s_addc_u32 s29, s57, s29
	global_load_dword v218, v[42:43], off
	global_load_dword v219, v[44:45], off
	v_lshl_add_u64 v[44:45], v[38:39], 0, s[30:31]
	s_or_b32 s30, s4, 7
	s_ashr_i32 s31, s30, 31
	s_lshl_b64 s[36:37], s[30:31], 11
	v_lshl_add_u64 v[38:39], v[38:39], 0, s[36:37]
	s_lshl_b64 s[30:31], s[30:31], 12
	s_add_u32 s30, s56, s30
	s_addc_u32 s31, s57, s31
	global_load_dword v220, v[44:45], off
	global_load_dword v221, v[38:39], off
	s_waitcnt vmcnt(7)
	v_mul_f32_e32 v37, 0xbfb8aa3b, v214
	v_exp_f32_e32 v37, v37
	s_nop 0
	v_add_f32_e32 v37, 1.0, v37
	v_rcp_f32_e32 v46, v37
	s_waitcnt vmcnt(6)
	v_mul_f32_e32 v37, 0xbfb8aa3b, v215
	v_exp_f32_e32 v37, v37
	s_nop 0
	v_add_f32_e32 v37, 1.0, v37
	v_rcp_f32_e32 v47, v37
	s_waitcnt vmcnt(5)
	v_mul_f32_e32 v37, 0xbfb8aa3b, v216
	v_exp_f32_e32 v37, v37
	s_nop 0
	v_add_f32_e32 v37, 1.0, v37
	v_rcp_f32_e32 v40, v37
	s_waitcnt vmcnt(4)
	v_mul_f32_e32 v37, 0xbfb8aa3b, v217
	v_exp_f32_e32 v37, v37
	s_nop 0
	v_add_f32_e32 v37, 1.0, v37
	v_rcp_f32_e32 v41, v37
	s_waitcnt vmcnt(3)
	v_mul_f32_e32 v37, 0xbfb8aa3b, v218
	v_exp_f32_e32 v37, v37
	s_nop 0
	v_add_f32_e32 v37, 1.0, v37
	v_rcp_f32_e32 v42, v37
	s_waitcnt vmcnt(2)
; #define LAS __attribute__((address_space(3)))
; __device__ __forceinline__ void hgrn_sample_loop(Frame& F) {
;     ...
;             for (int t = 0; t < 8; ++t) { const size_t tok = (size_t)(tok0 + t); const float fz = FZ[tok * 512 + col]; qq[t] = bf2f(PB[tok * PBW + 512 + col]);
;                 const float sg = __builtin_amdgcn_rcpf(1.0f + __builtin_amdgcn_exp2f(-1.4426950408889634f * fz)), f = lb + (1.0f - lb) * sg; kk[t] = 1.0f - f; run += __log2f(f); gl[t] = run; }
;             float qt[8], k3[8];
; #pragma unroll
;             for (int t = 0; t < 8; ++t) { qt[t] = qq[t] * __builtin_amdgcn_exp2f(gl[t]); k3[t] = kk[t] * __builtin_amdgcn_exp2f(run - gl[t]); Qs[t * 128 + tid] = qt[t]; K2[t * 128 + tid] = kk[t] * __builtin_amdgcn_exp2f(-gl[t]); }
;             *(LAS f32x4*)(QT + tid * 8) = (f32x4){qt[0], qt[1], qt[2], qt[3]}; *(LAS f32x4*)(QT + tid * 8 + 4) = (f32x4){qt[4], qt[5], qt[6], qt[7]};
;             *(LAS f32x4*)(K3T + tid * 8) = (f32x4){k3[0], k3[1], k3[2], k3[3]}; *(LAS f32x4*)(K3T + tid * 8 + 4) = (f32x4){k3[4], k3[5], k3[6], k3[7]};
;             DEC[tid] = __builtin_amdgcn_exp2f(run);
	v_mul_f32_e32 v37, 0xbfb8aa3b, v219
	v_exp_f32_e32 v37, v37
	s_nop 0
	v_add_f32_e32 v37, 1.0, v37
	v_rcp_f32_e32 v43, v37
	s_waitcnt vmcnt(1)
	v_mul_f32_e32 v37, 0xbfb8aa3b, v220
	v_exp_f32_e32 v37, v37
	s_nop 0
	v_add_f32_e32 v37, 1.0, v37
	v_rcp_f32_e32 v44, v37
	s_waitcnt vmcnt(0)
	v_mul_f32_e32 v37, 0xbfb8aa3b, v221
	v_exp_f32_e32 v37, v37
	s_nop 0
	v_add_f32_e32 v37, 1.0, v37
	v_rcp_f32_e32 v45, v37
	global_load_ushort v37, v35, s[18:19] offset:1024
	global_load_ushort v38, v35, s[16:17] offset:1024
	s_waitcnt vmcnt(1)
	v_pk_fma_f32 v[46:47], v[46:47], v[36:37], v[34:35] op_sel_hi:[1,0,0]
	global_load_ushort v51, v35, s[22:23] offset:1024
	global_load_ushort v52, v35, s[20:21] offset:1024
	global_load_ushort v53, v35, s[24:25] offset:1024
	global_load_ushort v55, v35, s[26:27] offset:1024
	global_load_ushort v56, v35, s[28:29] offset:1024
	s_nop 0
	global_load_ushort v35, v35, s[30:31] offset:1024
	v_lshlrev_b32_e32 v49, 16, v37
	v_log_f32_e32 v37, v46
	s_waitcnt vmcnt(6)
	v_lshlrev_b32_e32 v48, 16, v38
	v_pk_add_f32 v[38:39], v[46:47], 1.0 op_sel_hi:[1,0] neg_lo:[1,0] neg_hi:[1,0]
	v_log_f32_e32 v46, v47
	v_add_f32_e32 v37, 0, v37
	v_exp_f32_e64 v47, -v37
	v_add_f32_e32 v54, v37, v46
	v_exp_f32_e32 v46, v37
	v_mul_f32_e32 v50, v38, v47
	v_exp_f32_e32 v47, v54
	s_waitcnt vmcnt(0)
	v_pk_fma_f32 v[40:41], v[36:37], v[40:41], v[34:35] op_sel_hi:[0,1,0]
	v_pk_mul_f32 v[46:47], v[46:47], v[48:49]
	v_exp_f32_e64 v48, -v54
	v_lshlrev_b32_e32 v49, 16, v52
	v_log_f32_e32 v52, v40
	v_pk_fma_f32 v[42:43], v[36:37], v[42:43], v[34:35] op_sel_hi:[0,1,0]
	v_mul_f32_e32 v48, v39, v48
	ds_write2st64_b32 v133, v50, v48 offset0:16 offset1:18
	v_lshlrev_b32_e32 v48, 16, v51
	v_pk_add_f32 v[50:51], v[40:41], 1.0 op_sel_hi:[1,0] neg_lo:[1,0] neg_hi:[1,0]
	v_log_f32_e32 v40, v41
	v_add_f32_e32 v57, v54, v52
	v_exp_f32_e64 v41, -v57
	ds_write2st64_b32 v133, v46, v47 offset1:2
	v_add_f32_e32 v58, v57, v40
	v_exp_f32_e32 v40, v57
	v_mul_f32_e32 v52, v50, v41
	v_exp_f32_e32 v41, v58
	s_nop 0
	v_pk_mul_f32 v[48:49], v[40:41], v[48:49]
	v_exp_f32_e64 v40, -v58
	v_lshlrev_b32_e32 v41, 16, v55
	v_log_f32_e32 v55, v42
	ds_write2st64_b32 v133, v48, v49 offset0:4 offset1:6
	v_mul_f32_e32 v40, v51, v40
	ds_write2st64_b32 v133, v52, v40 offset0:20 offset1:22
	v_lshlrev_b32_e32 v40, 16, v53
	v_pk_add_f32 v[52:53], v[42:43], 1.0 op_sel_hi:[1,0] neg_lo:[1,0] neg_hi:[1,0]
	v_log_f32_e32 v42, v43
	v_add_f32_e32 v55, v58, v55
	v_exp_f32_e64 v43, -v55
	v_add_f32_e32 v59, v55, v42
	v_exp_f32_e32 v42, v55
	v_mul_f32_e32 v60, v52, v43
	v_exp_f32_e32 v43, v59
	s_nop 0
	v_pk_mul_f32 v[40:41], v[42:43], v[40:41]
	v_exp_f32_e64 v42, -v59
	v_lshlrev_b32_e32 v43, 16, v35
	v_pk_fma_f32 v[34:35], v[36:37], v[44:45], v[34:35] op_sel_hi:[0,1,0]
	v_log_f32_e32 v36, v34
	v_pk_add_f32 v[44:45], v[34:35], 1.0 op_sel_hi:[1,0] neg_lo:[1,0] neg_hi:[1,0]
	v_log_f32_e32 v34, v35
	v_mul_f32_e32 v42, v53, v42
	ds_write2st64_b32 v133, v60, v42 offset0:24 offset1:26
	v_add_f32_e32 v60, v59, v36
	v_add_f32_e32 v61, v60, v34
	v_sub_f32_e32 v36, v61, v57
	v_sub_f32_e32 v57, v61, v60
	v_sub_f32_e32 v34, v61, v37
	v_sub_f32_e32 v37, v61, v58
	v_exp_f32_e32 v58, v57
	v_exp_f32_e64 v57, -v60
	v_lshlrev_b32_e32 v42, 16, v56
	v_exp_f32_e32 v56, v60
	v_sub_f32_e32 v35, v61, v54
	v_mul_f32_e32 v60, v44, v57
	v_exp_f32_e32 v57, v61
	v_exp_f32_e32 v34, v34
	v_exp_f32_e32 v35, v35
	v_exp_f32_e32 v36, v36
	v_pk_mul_f32 v[42:43], v[56:57], v[42:43]
	v_sub_f32_e32 v56, v61, v61
	v_exp_f32_e32 v37, v37
	v_sub_f32_e32 v54, v61, v55
	v_sub_f32_e32 v55, v61, v59
	v_exp_f32_e32 v59, v56
	v_exp_f32_e64 v56, -v61
	v_exp_f32_e32 v54, v54
	v_exp_f32_e32 v55, v55
	v_pk_mul_f32 v[34:35], v[38:39], v[34:35]
	v_mul_f32_e32 v56, v45, v56
	v_pk_mul_f32 v[36:37], v[50:51], v[36:37]
	ds_write2st64_b32 v133, v40, v41 offset0:8 offset1:10
	ds_write2st64_b32 v133, v42, v43 offset0:12 offset1:14
	ds_write2st64_b32 v133, v60, v56 offset0:28 offset1:30
	ds_write_b128 v147, v[46:49] offset:8192
	ds_write_b128 v147, v[40:43] offset:8208
	ds_write_b128 v147, v[34:37] offset:12288
	v_pk_mul_f32 v[34:35], v[52:53], v[54:55]
	v_pk_mul_f32 v[36:37], v[44:45], v[58:59]
	ds_write_b128 v147, v[34:37] offset:12304
	ds_write_b32 v133, v57 offset:20480
